# phase C item assignment rebalanced at the loop edge: blocks owning a 7th heavy GDN item take 6 light (V-transpose/head-vector) items, the others ~13.4; every item still processed exactly once
# baseline (speedup 1.0000x reference)
.LBB0_404:
	v_readlane_b32 s1, v253, 0
	s_cmpk_gt_i32 s30, 0xcbf
	s_cbranch_scc1 .Lpc_light
	v_readlane_b32 s0, v253, 1
	s_add_i32 s30, s30, s0
	s_cmpk_gt_i32 s30, 0xcbf
	s_cbranch_scc0 .LBB0_405
	s_movk_i32 s0, 0xcc0
	s_movk_i32 vcc_lo, 0x1080
	s_cmpk_lt_u32 s1, 0xc0
	s_cselect_b32 s0, s0, vcc_lo
	s_add_i32 s30, s1, s0
	s_branch .LBB0_405
.Lpc_light:
	s_movk_i32 s0, 0xc0
	s_movk_i32 vcc_lo, 0x140
	s_movk_i32 vcc_hi, 0x1140
	s_cmpk_lt_u32 s1, 0xc0
	s_cselect_b32 s0, s0, vcc_lo
	s_movk_i32 vcc_lo, 0x2200
	s_cselect_b32 s1, vcc_hi, vcc_lo
	s_add_i32 s30, s30, s0
	s_cmp_lt_i32 s30, s1
	s_cbranch_scc1 .LBB0_405
	s_branch .LBB0_652
